# P4 router: second row's x loads issued together with the first row's (prefetched into spare registers)
# baseline (speedup 1.0000x reference)
; __device__ __forceinline__ unsigned pack2(float a, float b) { return (unsigned)f2bf(a) | ((unsigned)f2bf(b) << 16); }
; __device__ __forceinline__ void router_rows(const Params& p, char* smem, int l, int nrows) {
;     ...
;     for (int rr = 0; rr < 2; ++rr) {
;       const int rl = wid * 2 + rr;
;       const int row = grp * 8 + rl;
;       const float* src = XR + (size_t)row * 1024;
;       int v = row < MLAT ? (row >> 13) : 2;
;       const float* mods = (const float*)(ws + OFF_MODS) + (l * 3 + v) * 6144;
;       float4 xv[4];
;       float ss = 0.f;
; #pragma unroll
;       for (int q = 0; q < 4; ++q) {
;         xv[q] = *(const float4*)&src[lane * 4 + 256 * q];
;         ss += xv[q].x * xv[q].x + xv[q].y * xv[q].y + xv[q].z * xv[q].z + xv[q].w * xv[q].w;
;       }
;       ss = wave_sum(ss);
;       float rstd = rsqrtf(ss * (1.f / 1024.f) + EPSF);
; #pragma unroll
;       for (int q = 0; q < 4; ++q) {
;         int col = lane * 4 + 256 * q;
;         float4 w = *(const float4*)&nw[col];
;         float4 sh = *(const float4*)&mods[3072 + col];
;         float4 sc = *(const float4*)&mods[4096 + col];
;         float h0 = xv[q].x * rstd * w.x * (1.f + sc.x) + sh.x;
;         float h1 = xv[q].y * rstd * w.y * (1.f + sc.y) + sh.y;
;         float h2 = xv[q].z * rstd * w.z * (1.f + sc.z) + sh.z;
;         float h3 = xv[q].w * rstd * w.w * (1.f + sc.w) + sh.w;
;         uint2 o; o.x = pack2(h0, h1); o.y = pack2(h2, h3);
;         *(uint2*)&H2[(size_t)row * 1024 + col] = o;
;         *(float4*)&Hs[(col >> 2) * 36 + rl * 4] = make_float4(h0, h1, h2, h3);
;       }
.LBB0_1270:
	s_lshl_b32 s6, s9, 3
	v_add_u32_e32 v2, s6, v33
	v_min_i32_e32 v4, 0x4000, v2
	v_ashrrev_i32_e32 v4, 13, v4
	v_add_u32_e32 v4, s8, v4
	s_movk_i32 s7, 0x1800
	v_mul_lo_u32 v4, v4, s7
	v_ashrrev_i32_e32 v5, 31, v4
	v_lshl_add_u64 v[4:5], v[4:5], 2, v[22:23]
	s_movk_i32 s5, 0x3000
	v_add_co_u32_e32 v30, vcc, s5, v4
	v_ashrrev_i32_e32 v3, 31, v2
	s_nop 0
	v_addc_co_u32_e32 v31, vcc, 0, v5, vcc
	v_lshlrev_b64 v[6:7], 12, v[2:3]
	v_add_co_u32_e32 v28, vcc, s91, v4
	v_lshl_add_u64 v[74:75], v[20:21], 0, v[6:7]
	v_lshlrev_b64 v[2:3], 11, v[2:3]
	v_addc_co_u32_e32 v29, vcc, 0, v5, vcc
	s_barrier
	v_lshl_add_u64 v[26:27], v[24:25], 0, v[2:3]
	global_load_dwordx4 v[186:189], v[74:75], off
	global_load_dwordx4 v[190:193], v[18:19], off
	global_load_dwordx4 v[212:215], v[30:31], off
	global_load_dwordx4 v[216:219], v[28:29], off
	global_load_dwordx4 v[220:223], v[74:75], off offset:2048
	global_load_dwordx4 v[224:227], v[74:75], off offset:1024
	global_load_dwordx4 v[228:231], v[74:75], off offset:3072
	global_load_dwordx4 v[232:235], v[18:19], off offset:1024
	global_load_dwordx4 v[240:243], v[30:31], off offset:1024
	global_load_dwordx4 v[244:247], v[28:29], off offset:1024
	global_load_dwordx4 v[248:251], v[18:19], off offset:2048
	global_load_dwordx4 v[252:255], v[30:31], off offset:2048
	v_add_u32_e32 v144, s6, v67
	v_ashrrev_i32_e32 v145, 31, v144
	v_lshlrev_b64 v[144:145], 12, v[144:145]
	v_lshl_add_u64 v[144:145], v[20:21], 0, v[144:145]
	global_load_dwordx4 v[148:151], v[144:145], off
	global_load_dwordx4 v[152:155], v[144:145], off offset:1024
	global_load_dwordx4 v[156:159], v[144:145], off offset:2048
	global_load_dwordx4 v[160:163], v[144:145], off offset:3072
	s_waitcnt vmcnt(0)
	s_mov_b32 s4, 0x800000
	s_mov_b32 s92, 0x800000
	s_waitcnt lgkmcnt(0)
	v_mov_b32_e32 v40, v186
	v_mov_b32_e32 v42, v190
	v_mov_b32_e32 v43, v192
	v_mov_b32_e32 v39, v218
	v_mov_b32_e32 v4, v217
	v_mov_b32_e32 v8, v191
	v_mov_b32_e32 v5, v219
	v_pk_add_f32 v[50:51], v[4:5], 1.0 op_sel_hi:[1,0]
	v_mov_b32_e32 v46, v212
	v_mov_b32_e32 v47, v214
	v_mov_b32_e32 v12, v213
	v_mov_b32_e32 v10, v187
	v_mov_b32_e32 v38, v216
	v_mov_b32_e32 v2, v186
	v_pk_add_f32 v[44:45], v[38:39], 1.0 op_sel_hi:[1,0]
	v_mov_b32_e32 v41, v188
	v_mov_b32_e32 v48, v187
	v_mov_b32_e32 v49, v189
	v_mov_b32_e32 v34, v221
	v_mov_b32_e32 v35, v223
	s_waitcnt lgkmcnt(0)
	v_mov_b32_e32 v11, v225
	v_mov_b32_e32 v3, v224
	v_pk_mul_f32 v[10:11], v[10:11], v[10:11]
	v_mov_b32_e32 v38, v224
	v_pk_fma_f32 v[2:3], v[2:3], v[2:3], v[10:11]
	v_mov_b32_e32 v10, v188
	v_mov_b32_e32 v11, v226
	v_pk_fma_f32 v[2:3], v[10:11], v[10:11], v[2:3]
	v_mov_b32_e32 v10, v189
	v_mov_b32_e32 v11, v227
	v_pk_fma_f32 v[10:11], v[10:11], v[10:11], v[2:3]
	v_mov_b32_e32 v39, v226
	v_mov_b32_e32 v6, v225
	v_mov_b32_e32 v36, v220
	v_mov_b32_e32 v74, v220
	v_mov_b32_e32 v70, v221
	v_mov_b32_e32 v37, v222
	v_add_f32_e32 v10, v10, v11
	s_waitcnt lgkmcnt(0)
	v_mov_b32_e32 v71, v229
	v_mov_b32_e32 v75, v228
	v_pk_mul_f32 v[70:71], v[70:71], v[70:71]
	s_nop 0
	v_pk_fma_f32 v[70:71], v[74:75], v[74:75], v[70:71]
	v_mov_b32_e32 v74, v222
	v_mov_b32_e32 v75, v230
	v_pk_fma_f32 v[70:71], v[74:75], v[74:75], v[70:71]
	v_mov_b32_e32 v72, v223
	v_mov_b32_e32 v73, v231
	v_pk_fma_f32 v[70:71], v[72:73], v[72:73], v[70:71]
	s_nop 0
	v_add_f32_e32 v10, v10, v70
	v_add_f32_e32 v10, v10, v71
	ds_bpermute_b32 v11, v52, v10
	s_waitcnt lgkmcnt(0)
	v_add_f32_e32 v10, v10, v11
	ds_bpermute_b32 v11, v53, v10
	s_waitcnt lgkmcnt(0)
	v_add_f32_e32 v10, v10, v11
	ds_bpermute_b32 v11, v54, v10
	s_waitcnt lgkmcnt(0)
	v_add_f32_e32 v10, v10, v11
	ds_bpermute_b32 v11, v55, v10
	s_waitcnt lgkmcnt(0)
	v_add_f32_e32 v10, v10, v11
	ds_bpermute_b32 v11, v56, v10
	s_waitcnt lgkmcnt(0)
	v_add_f32_e32 v10, v10, v11
	ds_bpermute_b32 v11, v57, v10
	s_waitcnt lgkmcnt(0)
	v_add_f32_e32 v10, v10, v11
	v_fmamk_f32 v10, v10, 0x3a800000, v197
	v_cmp_gt_f32_e32 vcc, s4, v10
	v_mul_f32_e32 v11, 0x4b800000, v10
	s_nop 0
	v_cndmask_b32_e32 v10, v10, v11, vcc
	v_rsq_f32_e32 v10, v10
	s_nop 0
	v_mul_f32_e32 v11, 0x45800000, v10
	v_cndmask_b32_e32 v32, v10, v11, vcc
	v_pk_mul_f32 v[10:11], v[40:41], v[32:33] op_sel_hi:[1,0]
	v_mov_b32_e32 v7, v227
	v_pk_mul_f32 v[6:7], v[6:7], v[32:33] op_sel_hi:[1,0]
	v_pk_mul_f32 v[10:11], v[42:43], v[10:11]
	v_pk_mul_f32 v[36:37], v[36:37], v[32:33] op_sel_hi:[1,0]
	v_pk_fma_f32 v[40:41], v[44:45], v[10:11], v[46:47]
	v_pk_mul_f32 v[10:11], v[48:49], v[32:33] op_sel_hi:[1,0]
	v_pk_mul_f32 v[34:35], v[34:35], v[32:33] op_sel_hi:[1,0]
	v_mov_b32_e32 v9, v193
	v_pk_mul_f32 v[8:9], v[8:9], v[10:11]
	s_nop 0
	v_mov_b32_e32 v13, v215
	v_pk_fma_f32 v[10:11], v[50:51], v[8:9], v[12:13]
	v_and_b32_sdwa v9, v40, v198 dst_sel:DWORD dst_unused:UNUSED_PAD src0_sel:WORD_1 src1_sel:DWORD
	v_add3_u32 v12, v40, v9, s33
	v_and_b32_sdwa v9, v11, v198 dst_sel:DWORD dst_unused:UNUSED_PAD src0_sel:WORD_1 src1_sel:DWORD
	v_and_b32_sdwa v13, v10, v198 dst_sel:DWORD dst_unused:UNUSED_PAD src0_sel:WORD_1 src1_sel:DWORD
	v_and_b32_sdwa v8, v41, v198 dst_sel:DWORD dst_unused:UNUSED_PAD src0_sel:WORD_1 src1_sel:DWORD
	v_add3_u32 v9, v11, v9, s33
	v_add3_u32 v13, v10, v13, s33
	v_add3_u32 v8, v41, v8, s33
	v_and_b32_e32 v9, 0xffff0000, v9
	v_and_b32_e32 v13, 0xffff0000, v13
	v_or_b32_sdwa v9, v9, v8 dst_sel:DWORD dst_unused:UNUSED_PAD src0_sel:DWORD src1_sel:WORD_1
	v_or_b32_sdwa v8, v13, v12 dst_sel:DWORD dst_unused:UNUSED_PAD src0_sel:DWORD src1_sel:WORD_1
	global_store_dwordx2 v[26:27], v[8:9], off
	v_add_u32_e32 v12, v62, v63
	v_mov_b32_e32 v8, v40
	v_mov_b32_e32 v9, v10
	v_mov_b32_e32 v10, v41
	ds_write_b128 v12, v[8:11]
	v_pk_mul_f32 v[12:13], v[38:39], v[32:33] op_sel_hi:[1,0]
	v_mov_b32_e32 v38, v232
	v_mov_b32_e32 v39, v234
	v_pk_mul_f32 v[12:13], v[12:13], v[38:39]
	s_waitcnt lgkmcnt(0)
; __device__ __forceinline__ unsigned pack2(float a, float b) { return (unsigned)f2bf(a) | ((unsigned)f2bf(b) << 16); }
; __device__ __forceinline__ void router_rows(const Params& p, char* smem, int l, int nrows) {
;     ...
;     for (int rr = 0; rr < 2; ++rr) {
;       const int rl = wid * 2 + rr;
;       const int row = grp * 8 + rl;
;       const float* src = XR + (size_t)row * 1024;
;       int v = row < MLAT ? (row >> 13) : 2;
;       const float* mods = (const float*)(ws + OFF_MODS) + (l * 3 + v) * 6144;
;       float4 xv[4];
;       float ss = 0.f;
; #pragma unroll
;       for (int q = 0; q < 4; ++q) {
;         xv[q] = *(const float4*)&src[lane * 4 + 256 * q];
;         ss += xv[q].x * xv[q].x + xv[q].y * xv[q].y + xv[q].z * xv[q].z + xv[q].w * xv[q].w;
;       }
;       ss = wave_sum(ss);
;       float rstd = rsqrtf(ss * (1.f / 1024.f) + EPSF);
; #pragma unroll
;       for (int q = 0; q < 4; ++q) {
;         int col = lane * 4 + 256 * q;
;         float4 w = *(const float4*)&nw[col];
;         float4 sh = *(const float4*)&mods[3072 + col];
;         float4 sc = *(const float4*)&mods[4096 + col];
;         float h0 = xv[q].x * rstd * w.x * (1.f + sc.x) + sh.x;
;         float h1 = xv[q].y * rstd * w.y * (1.f + sc.y) + sh.y;
;         float h2 = xv[q].z * rstd * w.z * (1.f + sc.z) + sh.z;
;         float h3 = xv[q].w * rstd * w.w * (1.f + sc.w) + sh.w;
;         uint2 o; o.x = pack2(h0, h1); o.y = pack2(h2, h3);
;         *(uint2*)&H2[(size_t)row * 1024 + col] = o;
;         *(float4*)&Hs[(col >> 2) * 36 + rl * 4] = make_float4(h0, h1, h2, h3);
;       }
	v_mov_b32_e32 v38, v244
	v_mov_b32_e32 v39, v246
	v_pk_add_f32 v[38:39], v[38:39], 1.0 op_sel_hi:[1,0]
	v_mov_b32_e32 v48, v240
	v_mov_b32_e32 v49, v242
	v_mov_b32_e32 v10, v233
	v_mov_b32_e32 v46, v245
	v_pk_fma_f32 v[12:13], v[12:13], v[38:39], v[48:49]
	v_mov_b32_e32 v11, v235
	v_pk_mul_f32 v[6:7], v[6:7], v[10:11]
	v_mov_b32_e32 v47, v247
	v_pk_add_f32 v[8:9], v[46:47], 1.0 op_sel_hi:[1,0]
	v_mov_b32_e32 v42, v241
	v_mov_b32_e32 v43, v243
	v_pk_fma_f32 v[8:9], v[6:7], v[8:9], v[42:43]
	v_and_b32_sdwa v7, v12, v198 dst_sel:DWORD dst_unused:UNUSED_PAD src0_sel:WORD_1 src1_sel:DWORD
	v_add3_u32 v10, v12, v7, s33
	v_and_b32_sdwa v7, v9, v198 dst_sel:DWORD dst_unused:UNUSED_PAD src0_sel:WORD_1 src1_sel:DWORD
	v_and_b32_sdwa v11, v8, v198 dst_sel:DWORD dst_unused:UNUSED_PAD src0_sel:WORD_1 src1_sel:DWORD
	v_and_b32_sdwa v6, v13, v198 dst_sel:DWORD dst_unused:UNUSED_PAD src0_sel:WORD_1 src1_sel:DWORD
	v_add3_u32 v7, v9, v7, s33
	v_add3_u32 v11, v8, v11, s33
	v_add3_u32 v6, v13, v6, s33
	v_and_b32_e32 v7, 0xffff0000, v7
	v_and_b32_e32 v11, 0xffff0000, v11
	v_or_b32_sdwa v7, v7, v6 dst_sel:DWORD dst_unused:UNUSED_PAD src0_sel:DWORD src1_sel:WORD_1
	v_or_b32_sdwa v6, v11, v10 dst_sel:DWORD dst_unused:UNUSED_PAD src0_sel:DWORD src1_sel:WORD_1
	global_store_dwordx2 v[26:27], v[6:7], off offset:512
	v_add_u32_e32 v10, v62, v64
	v_mov_b32_e32 v6, v12
	v_mov_b32_e32 v7, v8
	v_mov_b32_e32 v8, v13
	ds_write_b128 v10, v[6:9]
	global_load_dwordx4 v[186:189], v[28:29], off offset:2048
	global_load_dwordx4 v[190:193], v[18:19], off offset:3072
	global_load_dwordx4 v[212:215], v[30:31], off offset:3072
	global_load_dwordx4 v[216:219], v[28:29], off offset:3072
	s_waitcnt vmcnt(0)
	v_mov_b32_e32 v42, v248
	v_mov_b32_e32 v43, v250
	v_pk_mul_f32 v[36:37], v[36:37], v[42:43]
	s_waitcnt lgkmcnt(0)
	v_mov_b32_e32 v42, v186
	v_mov_b32_e32 v43, v188
	v_pk_add_f32 v[42:43], v[42:43], 1.0 op_sel_hi:[1,0]
	v_mov_b32_e32 v44, v252
	v_mov_b32_e32 v45, v254
	v_mov_b32_e32 v8, v249
	v_mov_b32_e32 v40, v187
	v_pk_fma_f32 v[36:37], v[36:37], v[42:43], v[44:45]
	v_mov_b32_e32 v9, v251
	v_pk_mul_f32 v[6:7], v[34:35], v[8:9]
	v_mov_b32_e32 v41, v189
	v_pk_add_f32 v[8:9], v[40:41], 1.0 op_sel_hi:[1,0]
	v_mov_b32_e32 v12, v253
	v_mov_b32_e32 v13, v255
	v_pk_fma_f32 v[8:9], v[6:7], v[8:9], v[12:13]
	v_and_b32_sdwa v7, v36, v198 dst_sel:DWORD dst_unused:UNUSED_PAD src0_sel:WORD_1 src1_sel:DWORD
	v_add3_u32 v10, v36, v7, s33
	v_and_b32_sdwa v7, v9, v198 dst_sel:DWORD dst_unused:UNUSED_PAD src0_sel:WORD_1 src1_sel:DWORD
	v_and_b32_sdwa v11, v8, v198 dst_sel:DWORD dst_unused:UNUSED_PAD src0_sel:WORD_1 src1_sel:DWORD
	v_and_b32_sdwa v6, v37, v198 dst_sel:DWORD dst_unused:UNUSED_PAD src0_sel:WORD_1 src1_sel:DWORD
	v_add3_u32 v7, v9, v7, s33
	v_add3_u32 v11, v8, v11, s33
	v_add3_u32 v6, v37, v6, s33
	v_and_b32_e32 v7, 0xffff0000, v7
	v_and_b32_e32 v11, 0xffff0000, v11
	v_or_b32_sdwa v7, v7, v6 dst_sel:DWORD dst_unused:UNUSED_PAD src0_sel:DWORD src1_sel:WORD_1
	v_or_b32_sdwa v6, v11, v10 dst_sel:DWORD dst_unused:UNUSED_PAD src0_sel:DWORD src1_sel:WORD_1
	global_store_dwordx2 v[26:27], v[6:7], off offset:1024
	v_add_u32_e32 v10, v62, v65
	v_mov_b32_e32 v6, v36
	v_mov_b32_e32 v7, v8
	v_mov_b32_e32 v8, v37
	ds_write_b128 v10, v[6:9]
	s_nop 0
	v_mov_b32_e32 v34, v228
	v_mov_b32_e32 v35, v230
	v_pk_mul_f32 v[34:35], v[34:35], v[32:33] op_sel_hi:[1,0]
	v_mov_b32_e32 v4, v229
	v_mov_b32_e32 v5, v231
	v_pk_mul_f32 v[2:3], v[4:5], v[32:33] op_sel_hi:[1,0]
	v_mov_b32_e32 v36, v190
	v_mov_b32_e32 v37, v192
	v_pk_mul_f32 v[34:35], v[34:35], v[36:37]
	s_waitcnt lgkmcnt(0)
	v_mov_b32_e32 v36, v216
	v_mov_b32_e32 v37, v218
	v_pk_add_f32 v[36:37], v[36:37], 1.0 op_sel_hi:[1,0]
	v_mov_b32_e32 v38, v212
	v_mov_b32_e32 v39, v214
	v_mov_b32_e32 v8, v191
	v_mov_b32_e32 v30, v217
	v_pk_fma_f32 v[34:35], v[34:35], v[36:37], v[38:39]
	v_mov_b32_e32 v9, v193
	v_pk_mul_f32 v[2:3], v[2:3], v[8:9]
	v_mov_b32_e32 v31, v219
	v_pk_add_f32 v[4:5], v[30:31], 1.0 op_sel_hi:[1,0]
	v_mov_b32_e32 v12, v213
	v_mov_b32_e32 v13, v215
	v_pk_fma_f32 v[4:5], v[2:3], v[4:5], v[12:13]
	v_and_b32_sdwa v3, v34, v198 dst_sel:DWORD dst_unused:UNUSED_PAD src0_sel:WORD_1 src1_sel:DWORD
	v_add3_u32 v6, v34, v3, s33
	v_and_b32_sdwa v3, v5, v198 dst_sel:DWORD dst_unused:UNUSED_PAD src0_sel:WORD_1 src1_sel:DWORD
	v_and_b32_sdwa v7, v4, v198 dst_sel:DWORD dst_unused:UNUSED_PAD src0_sel:WORD_1 src1_sel:DWORD
	v_and_b32_sdwa v2, v35, v198 dst_sel:DWORD dst_unused:UNUSED_PAD src0_sel:WORD_1 src1_sel:DWORD
	v_add3_u32 v3, v5, v3, s33
	v_add3_u32 v7, v4, v7, s33
	v_add3_u32 v2, v35, v2, s33
	v_and_b32_e32 v3, 0xffff0000, v3
	v_and_b32_e32 v7, 0xffff0000, v7
	v_or_b32_sdwa v3, v3, v2 dst_sel:DWORD dst_unused:UNUSED_PAD src0_sel:DWORD src1_sel:WORD_1
	v_or_b32_sdwa v2, v7, v6 dst_sel:DWORD dst_unused:UNUSED_PAD src0_sel:DWORD src1_sel:WORD_1
	global_store_dwordx2 v[26:27], v[2:3], off offset:1536
	v_add_u32_e32 v6, v62, v66
	v_mov_b32_e32 v2, v34
	v_mov_b32_e32 v3, v4
	v_mov_b32_e32 v4, v35
	ds_write_b128 v6, v[2:5]
	v_add_u32_e32 v4, s6, v67
	v_min_i32_e32 v2, 0x4000, v4
	v_ashrrev_i32_e32 v2, 13, v2
	v_add_u32_e32 v2, s8, v2
	v_mul_lo_u32 v6, v2, s7
	v_ashrrev_i32_e32 v7, 31, v6
	v_lshl_add_u64 v[28:29], v[6:7], 2, v[22:23]
	v_add_co_u32_e32 v30, vcc, s5, v28
	v_ashrrev_i32_e32 v5, 31, v4
	s_nop 0
	v_addc_co_u32_e32 v31, vcc, 0, v29, vcc
	v_lshlrev_b64 v[2:3], 12, v[4:5]
	v_add_co_u32_e32 v28, vcc, s91, v28
	v_lshl_add_u64 v[2:3], v[20:21], 0, v[2:3]
	s_nop 0
	v_addc_co_u32_e32 v29, vcc, 0, v29, vcc
	v_mov_b64_e32 v[186:187], v[148:149]
	v_mov_b64_e32 v[188:189], v[150:151]
	global_load_dwordx4 v[190:193], v[18:19], off
	global_load_dwordx4 v[216:219], v[30:31], off
	global_load_dwordx4 v[220:223], v[28:29], off
	v_mov_b64_e32 v[224:225], v[152:153]
	v_mov_b64_e32 v[226:227], v[154:155]
	v_mov_b64_e32 v[228:229], v[156:157]
	v_mov_b64_e32 v[230:231], v[158:159]
	v_mov_b64_e32 v[232:233], v[160:161]
	v_mov_b64_e32 v[234:235], v[162:163]
	global_load_dwordx4 v[240:243], v[18:19], off offset:1024
	global_load_dwordx4 v[244:247], v[30:31], off offset:1024
	global_load_dwordx4 v[248:251], v[28:29], off offset:1024
	global_load_dwordx4 v[252:255], v[18:19], off offset:2048
	s_waitcnt vmcnt(0)
; __device__ __forceinline__ unsigned pack2(float a, float b) { return (unsigned)f2bf(a) | ((unsigned)f2bf(b) << 16); }
; __device__ __forceinline__ void router_rows(const Params& p, char* smem, int l, int nrows) {
;     ...
;       float4 xv[4];
;       float ss = 0.f;
; #pragma unroll
;       for (int q = 0; q < 4; ++q) {
;         xv[q] = *(const float4*)&src[lane * 4 + 256 * q];
;         ss += xv[q].x * xv[q].x + xv[q].y * xv[q].y + xv[q].z * xv[q].z + xv[q].w * xv[q].w;
;       }
;       ss = wave_sum(ss);
;       float rstd = rsqrtf(ss * (1.f / 1024.f) + EPSF);
; #pragma unroll
;       for (int q = 0; q < 4; ++q) {
;         int col = lane * 4 + 256 * q;
;         float4 w = *(const float4*)&nw[col];
;         float4 sh = *(const float4*)&mods[3072 + col];
;         float4 sc = *(const float4*)&mods[4096 + col];
;         float h0 = xv[q].x * rstd * w.x * (1.f + sc.x) + sh.x;
;         float h1 = xv[q].y * rstd * w.y * (1.f + sc.y) + sh.y;
;         float h2 = xv[q].z * rstd * w.z * (1.f + sc.z) + sh.z;
;         float h3 = xv[q].w * rstd * w.w * (1.f + sc.w) + sh.w;
;         uint2 o; o.x = pack2(h0, h1); o.y = pack2(h2, h3);
;         *(uint2*)&H2[(size_t)row * 1024 + col] = o;
;         *(float4*)&Hs[(col >> 2) * 36 + rl * 4] = make_float4(h0, h1, h2, h3);
;       }
	v_lshlrev_b64 v[4:5], 11, v[4:5]
	v_lshl_add_u64 v[26:27], v[24:25], 0, v[4:5]
	s_waitcnt lgkmcnt(0)
	v_mov_b32_e32 v40, v186
	v_mov_b32_e32 v42, v190
	v_mov_b32_e32 v43, v192
	v_mov_b32_e32 v4, v220
	v_mov_b32_e32 v5, v222
	v_pk_add_f32 v[44:45], v[4:5], 1.0 op_sel_hi:[1,0]
	v_mov_b32_e32 v8, v191
	v_mov_b32_e32 v72, v221
	v_mov_b32_e32 v46, v216
	v_mov_b32_e32 v48, v187
	v_mov_b32_e32 v73, v223
	v_pk_add_f32 v[50:51], v[72:73], 1.0 op_sel_hi:[1,0]
	v_mov_b32_e32 v10, v186
	v_mov_b32_e32 v34, v187
	v_mov_b32_e32 v47, v218
	v_mov_b32_e32 v12, v217
	v_mov_b32_e32 v41, v188
	v_mov_b32_e32 v49, v189
	s_waitcnt lgkmcnt(0)
	v_mov_b32_e32 v35, v225
	v_mov_b32_e32 v11, v224
	v_pk_mul_f32 v[34:35], v[34:35], v[34:35]
	v_mov_b32_e32 v38, v224
	v_pk_fma_f32 v[10:11], v[10:11], v[10:11], v[34:35]
	v_mov_b32_e32 v35, v226
	v_mov_b32_e32 v39, v226
	v_mov_b32_e32 v6, v225
	v_mov_b32_e32 v34, v188
	v_pk_fma_f32 v[10:11], v[34:35], v[34:35], v[10:11]
	v_mov_b32_e32 v34, v189
	v_mov_b32_e32 v35, v227
	v_pk_fma_f32 v[10:11], v[34:35], v[34:35], v[10:11]
	v_mov_b32_e32 v36, v228
	v_mov_b32_e32 v34, v229
	v_mov_b32_e32 v74, v228
	v_mov_b32_e32 v70, v229
	v_mov_b32_e32 v37, v230
	v_mov_b32_e32 v35, v231
	v_add_f32_e32 v10, v10, v11
	s_waitcnt lgkmcnt(0)
	v_mov_b32_e32 v71, v233
	v_mov_b32_e32 v75, v232
	v_pk_mul_f32 v[70:71], v[70:71], v[70:71]
	s_nop 0
	v_pk_fma_f32 v[70:71], v[74:75], v[74:75], v[70:71]
	v_mov_b32_e32 v74, v230
	v_mov_b32_e32 v75, v234
	v_pk_fma_f32 v[70:71], v[74:75], v[74:75], v[70:71]
	v_mov_b32_e32 v72, v231
	v_mov_b32_e32 v73, v235
	v_pk_fma_f32 v[70:71], v[72:73], v[72:73], v[70:71]
	s_nop 0
	v_add_f32_e32 v10, v10, v70
	v_add_f32_e32 v10, v10, v71
	ds_bpermute_b32 v11, v52, v10
	s_waitcnt lgkmcnt(0)
	v_add_f32_e32 v10, v10, v11
	ds_bpermute_b32 v11, v53, v10
	s_waitcnt lgkmcnt(0)
	v_add_f32_e32 v10, v10, v11
	ds_bpermute_b32 v11, v54, v10
	s_waitcnt lgkmcnt(0)
	v_add_f32_e32 v10, v10, v11
	ds_bpermute_b32 v11, v55, v10
	s_waitcnt lgkmcnt(0)
	v_add_f32_e32 v10, v10, v11
	ds_bpermute_b32 v11, v56, v10
	s_waitcnt lgkmcnt(0)
	v_add_f32_e32 v10, v10, v11
	ds_bpermute_b32 v11, v57, v10
	s_waitcnt lgkmcnt(0)
	v_add_f32_e32 v10, v10, v11
	v_fmamk_f32 v10, v10, 0x3a800000, v197
	v_cmp_gt_f32_e32 vcc, s4, v10
	v_mul_f32_e32 v11, 0x4b800000, v10
	s_mov_b64 s[4:5], 0
	v_cndmask_b32_e32 v10, v10, v11, vcc
	v_rsq_f32_e32 v10, v10
	s_nop 0
	v_mul_f32_e32 v11, 0x45800000, v10
	v_cndmask_b32_e32 v32, v10, v11, vcc
	v_pk_mul_f32 v[10:11], v[40:41], v[32:33] op_sel_hi:[1,0]
	v_mov_b32_e32 v7, v227
	v_pk_mul_f32 v[6:7], v[6:7], v[32:33] op_sel_hi:[1,0]
	v_pk_mul_f32 v[10:11], v[42:43], v[10:11]
	v_pk_mul_f32 v[36:37], v[36:37], v[32:33] op_sel_hi:[1,0]
	v_pk_fma_f32 v[40:41], v[44:45], v[10:11], v[46:47]
	v_pk_mul_f32 v[10:11], v[48:49], v[32:33] op_sel_hi:[1,0]
	v_pk_mul_f32 v[34:35], v[34:35], v[32:33] op_sel_hi:[1,0]
	v_mov_b32_e32 v9, v193
	v_pk_mul_f32 v[8:9], v[8:9], v[10:11]
	s_nop 0
	v_mov_b32_e32 v13, v219
	v_pk_fma_f32 v[10:11], v[50:51], v[8:9], v[12:13]
	v_and_b32_sdwa v9, v40, v198 dst_sel:DWORD dst_unused:UNUSED_PAD src0_sel:WORD_1 src1_sel:DWORD
	v_add3_u32 v12, v40, v9, s33
	v_and_b32_sdwa v9, v11, v198 dst_sel:DWORD dst_unused:UNUSED_PAD src0_sel:WORD_1 src1_sel:DWORD
	v_and_b32_sdwa v13, v10, v198 dst_sel:DWORD dst_unused:UNUSED_PAD src0_sel:WORD_1 src1_sel:DWORD
	v_and_b32_sdwa v8, v41, v198 dst_sel:DWORD dst_unused:UNUSED_PAD src0_sel:WORD_1 src1_sel:DWORD
	v_add3_u32 v9, v11, v9, s33
	v_add3_u32 v13, v10, v13, s33
	v_add3_u32 v8, v41, v8, s33
	v_and_b32_e32 v9, 0xffff0000, v9
	v_and_b32_e32 v13, 0xffff0000, v13
	v_or_b32_sdwa v9, v9, v8 dst_sel:DWORD dst_unused:UNUSED_PAD src0_sel:DWORD src1_sel:WORD_1
	v_or_b32_sdwa v8, v13, v12 dst_sel:DWORD dst_unused:UNUSED_PAD src0_sel:DWORD src1_sel:WORD_1
	global_store_dwordx2 v[26:27], v[8:9], off
	v_add_u32_e32 v12, v68, v63
	v_mov_b32_e32 v8, v40
	v_mov_b32_e32 v9, v10
	v_mov_b32_e32 v10, v41
	ds_write_b128 v12, v[8:11]
	v_pk_mul_f32 v[12:13], v[38:39], v[32:33] op_sel_hi:[1,0]
	v_mov_b32_e32 v38, v240
	v_mov_b32_e32 v39, v242
	v_pk_mul_f32 v[12:13], v[12:13], v[38:39]
	s_waitcnt lgkmcnt(0)
; __device__ __forceinline__ unsigned pack2(float a, float b) { return (unsigned)f2bf(a) | ((unsigned)f2bf(b) << 16); }
; __device__ __forceinline__ void router_rows(const Params& p, char* smem, int l, int nrows) {
;     ...
;       for (int q = 0; q < 4; ++q) {
;         int col = lane * 4 + 256 * q;
;         float4 w = *(const float4*)&nw[col];
;         float4 sh = *(const float4*)&mods[3072 + col];
;         float4 sc = *(const float4*)&mods[4096 + col];
;         float h0 = xv[q].x * rstd * w.x * (1.f + sc.x) + sh.x;
;         float h1 = xv[q].y * rstd * w.y * (1.f + sc.y) + sh.y;
;         float h2 = xv[q].z * rstd * w.z * (1.f + sc.z) + sh.z;
;         float h3 = xv[q].w * rstd * w.w * (1.f + sc.w) + sh.w;
;         uint2 o; o.x = pack2(h0, h1); o.y = pack2(h2, h3);
;         *(uint2*)&H2[(size_t)row * 1024 + col] = o;
;         *(float4*)&Hs[(col >> 2) * 36 + rl * 4] = make_float4(h0, h1, h2, h3);
;       }
;     }
;     __syncthreads();
;     {
;       const int e = tid & 15, ks = tid >> 4;
;       float acc[8];
; #pragma unroll
;       for (int r = 0; r < 8; ++r) acc[r] = 0.f;
	v_mov_b32_e32 v38, v248
	v_mov_b32_e32 v39, v250
	v_pk_add_f32 v[38:39], v[38:39], 1.0 op_sel_hi:[1,0]
	v_mov_b32_e32 v48, v244
	v_mov_b32_e32 v49, v246
	v_mov_b32_e32 v10, v241
	v_mov_b32_e32 v46, v249
	v_pk_fma_f32 v[12:13], v[12:13], v[38:39], v[48:49]
	v_mov_b32_e32 v11, v243
	v_pk_mul_f32 v[6:7], v[6:7], v[10:11]
	v_mov_b32_e32 v47, v251
	v_pk_add_f32 v[8:9], v[46:47], 1.0 op_sel_hi:[1,0]
	v_mov_b32_e32 v42, v245
	v_mov_b32_e32 v43, v247
	v_pk_fma_f32 v[8:9], v[6:7], v[8:9], v[42:43]
	v_and_b32_sdwa v7, v12, v198 dst_sel:DWORD dst_unused:UNUSED_PAD src0_sel:WORD_1 src1_sel:DWORD
	v_add3_u32 v10, v12, v7, s33
	v_and_b32_sdwa v7, v9, v198 dst_sel:DWORD dst_unused:UNUSED_PAD src0_sel:WORD_1 src1_sel:DWORD
	v_and_b32_sdwa v11, v8, v198 dst_sel:DWORD dst_unused:UNUSED_PAD src0_sel:WORD_1 src1_sel:DWORD
	v_and_b32_sdwa v6, v13, v198 dst_sel:DWORD dst_unused:UNUSED_PAD src0_sel:WORD_1 src1_sel:DWORD
	v_add3_u32 v7, v9, v7, s33
	v_add3_u32 v11, v8, v11, s33
	v_add3_u32 v6, v13, v6, s33
	v_and_b32_e32 v7, 0xffff0000, v7
	v_and_b32_e32 v11, 0xffff0000, v11
	v_or_b32_sdwa v7, v7, v6 dst_sel:DWORD dst_unused:UNUSED_PAD src0_sel:DWORD src1_sel:WORD_1
	v_or_b32_sdwa v6, v11, v10 dst_sel:DWORD dst_unused:UNUSED_PAD src0_sel:DWORD src1_sel:WORD_1
	global_store_dwordx2 v[26:27], v[6:7], off offset:512
	v_add_u32_e32 v10, v68, v64
	v_mov_b32_e32 v6, v12
	v_mov_b32_e32 v7, v8
	v_mov_b32_e32 v8, v13
	ds_write_b128 v10, v[6:9]
	global_load_dwordx4 v[186:189], v[30:31], off offset:2048
	global_load_dwordx4 v[190:193], v[28:29], off offset:2048
	global_load_dwordx4 v[212:215], v[18:19], off offset:3072
	global_load_dwordx4 v[216:219], v[30:31], off offset:3072
	global_load_dwordx4 v[220:223], v[28:29], off offset:3072
	s_waitcnt vmcnt(0)
	v_mov_b32_e32 v42, v252
	v_mov_b32_e32 v43, v254
	v_pk_mul_f32 v[36:37], v[36:37], v[42:43]
	s_waitcnt lgkmcnt(0)
	v_mov_b32_e32 v42, v190
	v_mov_b32_e32 v43, v192
	v_pk_add_f32 v[42:43], v[42:43], 1.0 op_sel_hi:[1,0]
	v_mov_b32_e32 v44, v186
	v_mov_b32_e32 v45, v188
	v_mov_b32_e32 v8, v253
	v_mov_b32_e32 v40, v191
	v_pk_fma_f32 v[36:37], v[36:37], v[42:43], v[44:45]
	v_mov_b32_e32 v9, v255
	v_pk_mul_f32 v[6:7], v[34:35], v[8:9]
	v_mov_b32_e32 v41, v193
	v_pk_add_f32 v[8:9], v[40:41], 1.0 op_sel_hi:[1,0]
	v_mov_b32_e32 v12, v187
	v_mov_b32_e32 v13, v189
	v_pk_fma_f32 v[8:9], v[6:7], v[8:9], v[12:13]
	v_and_b32_sdwa v7, v36, v198 dst_sel:DWORD dst_unused:UNUSED_PAD src0_sel:WORD_1 src1_sel:DWORD
	v_add3_u32 v10, v36, v7, s33
	v_and_b32_sdwa v7, v9, v198 dst_sel:DWORD dst_unused:UNUSED_PAD src0_sel:WORD_1 src1_sel:DWORD
	v_and_b32_sdwa v11, v8, v198 dst_sel:DWORD dst_unused:UNUSED_PAD src0_sel:WORD_1 src1_sel:DWORD
	v_and_b32_sdwa v6, v37, v198 dst_sel:DWORD dst_unused:UNUSED_PAD src0_sel:WORD_1 src1_sel:DWORD
	v_add3_u32 v7, v9, v7, s33
	v_add3_u32 v11, v8, v11, s33
	v_add3_u32 v6, v37, v6, s33
	v_and_b32_e32 v7, 0xffff0000, v7
	v_and_b32_e32 v11, 0xffff0000, v11
	v_or_b32_sdwa v7, v7, v6 dst_sel:DWORD dst_unused:UNUSED_PAD src0_sel:DWORD src1_sel:WORD_1
	v_or_b32_sdwa v6, v11, v10 dst_sel:DWORD dst_unused:UNUSED_PAD src0_sel:DWORD src1_sel:WORD_1
	global_store_dwordx2 v[26:27], v[6:7], off offset:1024
	v_add_u32_e32 v10, v68, v65
	v_mov_b32_e32 v6, v36
	v_mov_b32_e32 v7, v8
	v_mov_b32_e32 v8, v37
	ds_write_b128 v10, v[6:9]
	s_nop 0
	v_mov_b32_e32 v34, v232
	v_mov_b32_e32 v35, v234
	v_pk_mul_f32 v[34:35], v[34:35], v[32:33] op_sel_hi:[1,0]
	v_mov_b32_e32 v4, v233
	v_mov_b32_e32 v5, v235
	v_pk_mul_f32 v[2:3], v[4:5], v[32:33] op_sel_hi:[1,0]
	v_mov_b32_e32 v36, v212
	v_mov_b32_e32 v37, v214
	v_pk_mul_f32 v[34:35], v[34:35], v[36:37]
	s_waitcnt lgkmcnt(0)
	v_mov_b32_e32 v36, v220
	v_mov_b32_e32 v37, v222
	v_pk_add_f32 v[36:37], v[36:37], 1.0 op_sel_hi:[1,0]
	v_mov_b32_e32 v38, v216
	v_mov_b32_e32 v39, v218
	v_mov_b32_e32 v8, v213
	v_mov_b32_e32 v30, v221
	v_pk_fma_f32 v[34:35], v[34:35], v[36:37], v[38:39]
	v_mov_b32_e32 v9, v215
	v_pk_mul_f32 v[2:3], v[2:3], v[8:9]
	v_mov_b32_e32 v31, v223
	v_pk_add_f32 v[4:5], v[30:31], 1.0 op_sel_hi:[1,0]
	v_mov_b32_e32 v12, v217
	v_mov_b32_e32 v13, v219
	v_pk_fma_f32 v[4:5], v[2:3], v[4:5], v[12:13]
	v_and_b32_sdwa v3, v34, v198 dst_sel:DWORD dst_unused:UNUSED_PAD src0_sel:WORD_1 src1_sel:DWORD
	v_add3_u32 v6, v34, v3, s33
	v_and_b32_sdwa v3, v5, v198 dst_sel:DWORD dst_unused:UNUSED_PAD src0_sel:WORD_1 src1_sel:DWORD
	v_and_b32_sdwa v7, v4, v198 dst_sel:DWORD dst_unused:UNUSED_PAD src0_sel:WORD_1 src1_sel:DWORD
	v_and_b32_sdwa v2, v35, v198 dst_sel:DWORD dst_unused:UNUSED_PAD src0_sel:WORD_1 src1_sel:DWORD
	v_add3_u32 v3, v5, v3, s33
	v_add3_u32 v7, v4, v7, s33
	v_add3_u32 v2, v35, v2, s33
	v_and_b32_e32 v3, 0xffff0000, v3
	v_and_b32_e32 v7, 0xffff0000, v7
	v_or_b32_sdwa v3, v3, v2 dst_sel:DWORD dst_unused:UNUSED_PAD src0_sel:DWORD src1_sel:WORD_1
	v_or_b32_sdwa v2, v7, v6 dst_sel:DWORD dst_unused:UNUSED_PAD src0_sel:DWORD src1_sel:WORD_1
	global_store_dwordx2 v[26:27], v[2:3], off offset:1536
	v_add_u32_e32 v6, v68, v66
	v_mov_b32_e32 v2, v34
	v_mov_b32_e32 v3, v4
	v_mov_b32_e32 v4, v35
	ds_write_b128 v6, v[2:5]
	v_mov_b32_e32 v6, 0
	v_mov_b32_e32 v10, v0
	v_mov_b32_e32 v7, v6
	v_mov_b32_e32 v8, v6
	v_mov_b32_e32 v9, v6
	v_mov_b32_e32 v4, v6
	v_mov_b32_e32 v5, v6
	v_mov_b32_e32 v2, v6
	v_mov_b32_e32 v3, v6
	s_waitcnt lgkmcnt(0)
	v_mov_b32_e32 v11, v217
	v_mov_b32_e32 v28, v220
	v_mov_b32_e32 v29, v221
	s_barrier
